# in_proj units paired (Q,U) and (K,V) per workgroup
# speedup vs baseline: 1.0051x; 1.0051x over previous
.Lxbn1_end:
.LBB0_186:
	s_or_b64 exec, exec, s[4:5]
	s_mov_b64 s[16:17], s[0:1]
	s_waitcnt lgkmcnt(0)
	s_barrier
	s_load_dwordx2 s[18:19], s[16:17], 0xe8
	v_mov_b32_e32 v14, v170
	s_cmpk_lt_i32 s2, 0x180
	s_cselect_b64 s[4:5], -1, 0
	s_cmpk_gt_i32 s2, 0x17f
	v_readfirstlane_b32 s45, v14
	s_cbranch_scc1 .LBB0_188
	s_ashr_i32 s3, s2, 31
	s_lshr_b32 s3, s3, 29
	s_add_i32 s3, s2, s3
	s_ashr_i32 s6, s3, 3
	s_and_b32 s3, s3, -8
	s_sub_i32 s3, s2, s3
	s_lshr_b32 s7, s3, 31
	s_or_b32 s7, s7, 48
	s_mul_i32 s3, s7, s3
	s_add_i32 s3, s3, s6
	s_ashr_i32 s6, s3, 31
	s_lshr_b32 s6, s6, 26
	s_add_i32 s6, s3, s6
	s_ashr_i32 s6, s6, 6
	s_lshl_b32 s8, s6, 3
	s_sub_i32 s7, 48, s8
	s_lshl_b32 s6, s6, 6
	s_min_u32 s9, s7, 8
	s_sub_i32 s3, s3, s6
	s_sext_i32_i8 s6, s3
	v_cvt_f32_ubyte0_e32 v1, s9
	v_cvt_f32_i32_e32 v0, s6
	v_rcp_iflag_f32_e32 v2, v1
	s_ashr_i32 s6, s6, 30
	s_or_b32 s10, s6, 1
	v_mul_f32_e32 v2, v0, v2
	v_trunc_f32_e32 v2, v2
	v_fma_f32 v0, -v2, v1, v0
	v_cvt_i32_f32_e32 v2, v2
	v_cmp_ge_f32_e64 s[6:7], |v0|, v1
	s_and_b64 s[6:7], s[6:7], exec
	s_cselect_b32 s6, s10, 0
	v_readfirstlane_b32 s7, v2
	s_add_i32 s6, s7, s6
	s_sext_i32_i8 s12, s6
	s_mul_i32 s6, s6, s9
	s_sub_i32 s3, s3, s6
	s_sext_i32_i8 s3, s3
	s_add_i32 s10, s8, s3
	s_and_b32 s3, s12, 4
	s_lshr_b32 s3, s3, 1
	s_xor_b32 s12, s12, s3

.LBB0_193:
	s_add_i32 s79, s79, 1
	s_mul_i32 s6, s79, s69
	s_mul_hi_u32 s7, s79, s70
	s_add_i32 s7, s7, s6
	s_mul_i32 s6, s79, s70
	s_add_u32 s36, s6, s2
	s_addc_u32 s37, s7, s3
	v_cmp_gt_i64_e64 s[6:7], s[36:37], v[142:143]
	s_and_b64 vcc, exec, s[6:7]
	s_cbranch_vccnz .LBB0_195
	s_ashr_i32 s11, s36, 31
	s_lshr_b32 s11, s11, 29
	s_add_i32 s11, s36, s11
	s_ashr_i32 s13, s11, 3
	s_and_b32 s11, s11, -8
	s_sub_i32 s11, s36, s11
	s_lshr_b32 s30, s11, 31
	s_or_b32 s30, s30, 48
	s_mul_i32 s11, s30, s11
	s_add_i32 s11, s11, s13
	s_ashr_i32 s13, s11, 31
	s_lshr_b32 s13, s13, 26
	s_add_i32 s13, s11, s13
	s_ashr_i32 s30, s13, 6
	s_lshl_b32 s31, s30, 3
	s_sub_i32 s30, 48, s31
	s_min_i32 s33, s30, 8
	s_abs_i32 s30, s33
	v_cvt_f32_u32_e32 v0, s30
	s_sub_i32 s35, 0, s30
	s_andn2_b32 s13, s13, 63
	s_sub_i32 s11, s11, s13
	v_rcp_iflag_f32_e32 v0, v0
	s_abs_i32 s13, s11
	s_xor_b32 s34, s11, s33
	s_ashr_i32 s34, s34, 31
	v_mul_f32_e32 v0, 0x4f7ffffe, v0
	v_cvt_u32_f32_e32 v0, v0
	s_nop 0
	v_readfirstlane_b32 s40, v0
	s_mul_i32 s35, s35, s40
	s_mul_hi_u32 s35, s40, s35
	s_add_i32 s40, s40, s35
	s_mul_hi_u32 s35, s13, s40
	s_mul_i32 s40, s35, s30
	s_sub_i32 s13, s13, s40
	s_add_i32 s41, s35, 1
	s_sub_i32 s40, s13, s30
	s_cmp_ge_u32 s13, s30
	s_cselect_b32 s35, s41, s35
	s_cselect_b32 s13, s40, s13
	s_add_i32 s40, s35, 1
	s_cmp_ge_u32 s13, s30
	s_cselect_b32 s13, s40, s35
	s_xor_b32 s13, s13, s34
	s_sub_i32 s30, s13, s34
	s_mul_i32 s13, s30, s33
	s_sub_i32 s11, s11, s13
	s_add_i32 s34, s11, s31
	s_and_b32 s11, s30, 4
	s_lshr_b32 s11, s11, 1
	s_xor_b32 s30, s30, s11
